# final RMSNorm phase rewritten by hand: 4-row groups per wave software-pipelined, norm gain loaded once
# speedup vs baseline: 1.0203x; 1.0001x over previous
.LBB0_2128:
	s_or_b64 exec, exec, s[2:3]
	s_waitcnt lgkmcnt(0)
	s_barrier
	s_mov_b32 s0, 0x8000
	s_waitcnt vmcnt(3)
	v_ashrrev_i32_e32 v0, 6, v204
	v_add_u32_e32 v0, s72, v0
	v_cmp_gt_i32_e32 vcc, s0, v0
	s_and_saveexec_b64 s[0:1], vcc
	s_cbranch_execz .LBB0_2131
	s_load_dwordx4 s[4:7], s[70:71], 0xb0
	s_load_dwordx2 s[2:3], s[70:71], 0x18
	v_lshlrev_b32_e32 v1, 3, v204
	v_and_b32_e32 v1, 0x1f8, v1
	s_waitcnt vmcnt(2)
	v_lshlrev_b32_e32 v6, 1, v1
	s_waitcnt lgkmcnt(0)
	s_add_u32 s0, s6, 0x1ff00000
	v_mov_b32_e32 v7, 0
	s_addc_u32 s1, s7, 0
	v_lshl_add_u64 v[2:3], s[6:7], 0, v[6:7]
	s_mov_b64 s[6:7], 0x3a00000
	v_lshlrev_b32_e32 v6, 2, v1
	v_lshl_add_u64 v[2:3], v[2:3], 0, s[6:7]
	v_lshl_add_u64 v[4:5], s[4:5], 0, v[6:7]
	v_lshl_add_u64 v[6:7], s[2:3], 0, v[6:7]
	s_mov_b64 s[2:3], 0
	v_mov_b32_e32 v8, 0x358637bd
	s_mov_b32 s4, 0x800000
	s_movk_i32 s5, 0x7fff
	s_load_dwordx2 s[12:13], s[70:71], 0xb8
	s_load_dwordx2 s[16:17], s[70:71], 0xb0
	v_readfirstlane_b32 s8, v0
	s_mov_b32 s41, s83
	s_lshl_b32 s42, s83, 1
	s_mul_i32 s43, s83, 3
	s_lshl_b32 s47, s83, 2
	s_mov_b32 s44, 0x8000
	s_nop 3
	s_add_u32 s10, s8, s43
	s_cmp_lt_u32 s10, s44
	s_cbranch_scc0 .Lfn_skip
	v_and_b32_e32 v48, 63, v204
	v_lshlrev_b32_e32 v50, 5, v48
	v_lshlrev_b32_e32 v48, 4, v48
	v_mov_b32_e32 v49, 0
	global_load_dwordx4 v[32:35], v[6:7], off
	global_load_dwordx4 v[36:39], v[6:7], off offset:16
	global_load_dwordx4 v[40:43], v[6:7], off offset:2048
	global_load_dwordx4 v[44:47], v[6:7], off offset:2064
	s_waitcnt lgkmcnt(0)
	s_add_u32 s12, s12, 0x3a00000
	s_addc_u32 s13, s13, 0
	s_mov_b32 s11, s8
	s_lshl_b32 s37, s11, 3
	s_add_u32 s38, s0, s37
	s_addc_u32 s39, s1, 0
	global_load_dwordx2 v[64:65], v49, s[38:39]
	s_lshl_b32 s37, s11, 11
	s_add_u32 s38, s12, s37
	s_addc_u32 s39, s13, 0
	global_load_dwordx4 v[66:69], v48, s[38:39]
	global_load_dwordx4 v[70:73], v48, s[38:39] offset:1024
	s_lshl_b32 s37, s11, 12
	s_add_u32 s20, s16, s37
	s_addc_u32 s21, s17, 0
	s_add_u32 s11, s8, s41
	s_lshl_b32 s37, s11, 3
	s_add_u32 s38, s0, s37
	s_addc_u32 s39, s1, 0
	global_load_dwordx2 v[74:75], v49, s[38:39]
	s_lshl_b32 s37, s11, 11
	s_add_u32 s38, s12, s37
	s_addc_u32 s39, s13, 0
	global_load_dwordx4 v[76:79], v48, s[38:39]
	global_load_dwordx4 v[80:83], v48, s[38:39] offset:1024
	s_lshl_b32 s37, s11, 12
	s_add_u32 s22, s16, s37
	s_addc_u32 s23, s17, 0
	s_add_u32 s11, s8, s42
	s_lshl_b32 s37, s11, 3
	s_add_u32 s38, s0, s37
	s_addc_u32 s39, s1, 0
	global_load_dwordx2 v[84:85], v49, s[38:39]
	s_lshl_b32 s37, s11, 11
	s_add_u32 s38, s12, s37
	s_addc_u32 s39, s13, 0
	global_load_dwordx4 v[86:89], v48, s[38:39]
	global_load_dwordx4 v[90:93], v48, s[38:39] offset:1024
	s_lshl_b32 s37, s11, 12
	s_add_u32 s24, s16, s37
	s_addc_u32 s25, s17, 0
	s_add_u32 s11, s8, s43
	s_lshl_b32 s37, s11, 3
	s_add_u32 s38, s0, s37
	s_addc_u32 s39, s1, 0
	global_load_dwordx2 v[94:95], v49, s[38:39]
	s_lshl_b32 s37, s11, 11
	s_add_u32 s38, s12, s37
	s_addc_u32 s39, s13, 0
	global_load_dwordx4 v[96:99], v48, s[38:39]
	global_load_dwordx4 v[100:103], v48, s[38:39] offset:1024
	s_lshl_b32 s37, s11, 12
	s_add_u32 s26, s16, s37
	s_addc_u32 s27, s17, 0
	s_add_u32 s8, s8, s47
	s_mov_b32 s36, 1
.Lfn_pa:
	s_add_u32 s10, s8, s43
	s_cmp_lt_u32 s10, s44
	s_cselect_b32 s45, 1, 0
	s_sub_u32 s46, s8, s47
	s_cmp_eq_u32 s45, 1
	s_cselect_b32 s46, s8, s46
	s_mov_b32 s11, s46
	s_lshl_b32 s37, s11, 3
	s_add_u32 s38, s0, s37
	s_addc_u32 s39, s1, 0
	global_load_dwordx2 v[104:105], v49, s[38:39]
	s_lshl_b32 s37, s11, 11
	s_add_u32 s38, s12, s37
	s_addc_u32 s39, s13, 0
	global_load_dwordx4 v[106:109], v48, s[38:39]
	global_load_dwordx4 v[110:113], v48, s[38:39] offset:1024
	s_lshl_b32 s37, s11, 12
	s_add_u32 s28, s16, s37
	s_addc_u32 s29, s17, 0
	s_add_u32 s11, s46, s41
	s_lshl_b32 s37, s11, 3
	s_add_u32 s38, s0, s37
	s_addc_u32 s39, s1, 0
	global_load_dwordx2 v[114:115], v49, s[38:39]
	s_lshl_b32 s37, s11, 11
	s_add_u32 s38, s12, s37
	s_addc_u32 s39, s13, 0
	global_load_dwordx4 v[116:119], v48, s[38:39]
	global_load_dwordx4 v[120:123], v48, s[38:39] offset:1024
	s_lshl_b32 s37, s11, 12
	s_add_u32 s30, s16, s37
	s_addc_u32 s31, s17, 0
	s_add_u32 s11, s46, s42
	s_lshl_b32 s37, s11, 3
	s_add_u32 s38, s0, s37
	s_addc_u32 s39, s1, 0
	global_load_dwordx2 v[124:125], v49, s[38:39]
	s_lshl_b32 s37, s11, 11
	s_add_u32 s38, s12, s37
	s_addc_u32 s39, s13, 0
	global_load_dwordx4 v[126:129], v48, s[38:39]
	global_load_dwordx4 v[130:133], v48, s[38:39] offset:1024
	s_lshl_b32 s37, s11, 12
	s_add_u32 s32, s16, s37
	s_addc_u32 s33, s17, 0
	s_add_u32 s11, s46, s43
	s_lshl_b32 s37, s11, 3
	s_add_u32 s38, s0, s37
	s_addc_u32 s39, s1, 0
	global_load_dwordx2 v[134:135], v49, s[38:39]
	s_lshl_b32 s37, s11, 11
	s_add_u32 s38, s12, s37
	s_addc_u32 s39, s13, 0
	global_load_dwordx4 v[136:139], v48, s[38:39]
	global_load_dwordx4 v[140:143], v48, s[38:39] offset:1024
	s_lshl_b32 s37, s11, 12
	s_add_u32 s34, s16, s37
	s_addc_u32 s35, s17, 0
	s_cmp_eq_u32 s36, 1
	s_cbranch_scc1 .Lfn_pa_w12
	s_waitcnt vmcnt(28)
	s_branch .Lfn_pa_go
.Lfn_pa_w12:
	s_waitcnt vmcnt(12)
.Lfn_pa_go:
	s_mov_b32 s36, 0
	v_ffbh_u32_e32 v24, v65
	v_min_u32_e32 v24, 32, v24
	v_lshlrev_b64 v[64:65], v24, v[64:65]
	v_min_u32_e32 v64, 1, v64
	v_or_b32_e32 v65, v65, v64
	v_cvt_f32_u32_e32 v65, v65
	v_sub_u32_e32 v24, 32, v24
	v_ldexp_f32 v65, v65, v24
	v_fmamk_f32 v65, v65, 0x2e800000, v8
	v_rsq_f32_e32 v30, v65
	v_lshlrev_b32_e32 v16, 16, v66
	v_and_b32_e32 v17, 0xffff0000, v66
	v_lshlrev_b32_e32 v18, 16, v67
	v_and_b32_e32 v19, 0xffff0000, v67
	v_lshlrev_b32_e32 v20, 16, v68
	v_and_b32_e32 v21, 0xffff0000, v68
	v_lshlrev_b32_e32 v22, 16, v69
	v_and_b32_e32 v23, 0xffff0000, v69
	v_pk_mul_f32 v[16:17], v[30:31], v[16:17] op_sel_hi:[0,1]
	v_pk_mul_f32 v[18:19], v[30:31], v[18:19] op_sel_hi:[0,1]
	v_pk_mul_f32 v[20:21], v[30:31], v[20:21] op_sel_hi:[0,1]
	v_pk_mul_f32 v[22:23], v[30:31], v[22:23] op_sel_hi:[0,1]
	v_pk_mul_f32 v[16:17], v[32:33], v[16:17]
	v_pk_mul_f32 v[18:19], v[34:35], v[18:19]
	v_pk_mul_f32 v[20:21], v[36:37], v[20:21]
	v_pk_mul_f32 v[22:23], v[38:39], v[22:23]
	global_store_dwordx4 v50, v[16:19], s[20:21] offset:0
	global_store_dwordx4 v50, v[20:23], s[20:21] offset:16
	s_nop 1
	v_lshlrev_b32_e32 v16, 16, v70
	v_and_b32_e32 v17, 0xffff0000, v70
	v_lshlrev_b32_e32 v18, 16, v71
	v_and_b32_e32 v19, 0xffff0000, v71
	v_lshlrev_b32_e32 v20, 16, v72
	v_and_b32_e32 v21, 0xffff0000, v72
	v_lshlrev_b32_e32 v22, 16, v73
	v_and_b32_e32 v23, 0xffff0000, v73
	v_pk_mul_f32 v[16:17], v[30:31], v[16:17] op_sel_hi:[0,1]
	v_pk_mul_f32 v[18:19], v[30:31], v[18:19] op_sel_hi:[0,1]
	v_pk_mul_f32 v[20:21], v[30:31], v[20:21] op_sel_hi:[0,1]
	v_pk_mul_f32 v[22:23], v[30:31], v[22:23] op_sel_hi:[0,1]
	v_pk_mul_f32 v[16:17], v[40:41], v[16:17]
	v_pk_mul_f32 v[18:19], v[42:43], v[18:19]
	v_pk_mul_f32 v[20:21], v[44:45], v[20:21]
	v_pk_mul_f32 v[22:23], v[46:47], v[22:23]
	global_store_dwordx4 v50, v[16:19], s[20:21] offset:2048
	global_store_dwordx4 v50, v[20:23], s[20:21] offset:2064
	s_nop 1
	v_ffbh_u32_e32 v24, v75
	v_min_u32_e32 v24, 32, v24
	v_lshlrev_b64 v[74:75], v24, v[74:75]
	v_min_u32_e32 v74, 1, v74
	v_or_b32_e32 v75, v75, v74
	v_cvt_f32_u32_e32 v75, v75
	v_sub_u32_e32 v24, 32, v24
	v_ldexp_f32 v75, v75, v24
	v_fmamk_f32 v75, v75, 0x2e800000, v8
	v_rsq_f32_e32 v30, v75
	v_lshlrev_b32_e32 v16, 16, v76
	v_and_b32_e32 v17, 0xffff0000, v76
	v_lshlrev_b32_e32 v18, 16, v77
	v_and_b32_e32 v19, 0xffff0000, v77
	v_lshlrev_b32_e32 v20, 16, v78
	v_and_b32_e32 v21, 0xffff0000, v78
	v_lshlrev_b32_e32 v22, 16, v79
	v_and_b32_e32 v23, 0xffff0000, v79
	v_pk_mul_f32 v[16:17], v[30:31], v[16:17] op_sel_hi:[0,1]
	v_pk_mul_f32 v[18:19], v[30:31], v[18:19] op_sel_hi:[0,1]
	v_pk_mul_f32 v[20:21], v[30:31], v[20:21] op_sel_hi:[0,1]
	v_pk_mul_f32 v[22:23], v[30:31], v[22:23] op_sel_hi:[0,1]
	v_pk_mul_f32 v[16:17], v[32:33], v[16:17]
	v_pk_mul_f32 v[18:19], v[34:35], v[18:19]
	v_pk_mul_f32 v[20:21], v[36:37], v[20:21]
	v_pk_mul_f32 v[22:23], v[38:39], v[22:23]
	global_store_dwordx4 v50, v[16:19], s[22:23] offset:0
	global_store_dwordx4 v50, v[20:23], s[22:23] offset:16
	s_nop 1
	v_lshlrev_b32_e32 v16, 16, v80
	v_and_b32_e32 v17, 0xffff0000, v80
	v_lshlrev_b32_e32 v18, 16, v81
	v_and_b32_e32 v19, 0xffff0000, v81
	v_lshlrev_b32_e32 v20, 16, v82
	v_and_b32_e32 v21, 0xffff0000, v82
	v_lshlrev_b32_e32 v22, 16, v83
	v_and_b32_e32 v23, 0xffff0000, v83
	v_pk_mul_f32 v[16:17], v[30:31], v[16:17] op_sel_hi:[0,1]
	v_pk_mul_f32 v[18:19], v[30:31], v[18:19] op_sel_hi:[0,1]
	v_pk_mul_f32 v[20:21], v[30:31], v[20:21] op_sel_hi:[0,1]
	v_pk_mul_f32 v[22:23], v[30:31], v[22:23] op_sel_hi:[0,1]
	v_pk_mul_f32 v[16:17], v[40:41], v[16:17]
	v_pk_mul_f32 v[18:19], v[42:43], v[18:19]
	v_pk_mul_f32 v[20:21], v[44:45], v[20:21]
	v_pk_mul_f32 v[22:23], v[46:47], v[22:23]
	global_store_dwordx4 v50, v[16:19], s[22:23] offset:2048
	global_store_dwordx4 v50, v[20:23], s[22:23] offset:2064
	s_nop 1
	v_ffbh_u32_e32 v24, v85
	v_min_u32_e32 v24, 32, v24
	v_lshlrev_b64 v[84:85], v24, v[84:85]
	v_min_u32_e32 v84, 1, v84
	v_or_b32_e32 v85, v85, v84
	v_cvt_f32_u32_e32 v85, v85
	v_sub_u32_e32 v24, 32, v24
	v_ldexp_f32 v85, v85, v24
	v_fmamk_f32 v85, v85, 0x2e800000, v8
	v_rsq_f32_e32 v30, v85
	v_lshlrev_b32_e32 v16, 16, v86
	v_and_b32_e32 v17, 0xffff0000, v86
	v_lshlrev_b32_e32 v18, 16, v87
	v_and_b32_e32 v19, 0xffff0000, v87
	v_lshlrev_b32_e32 v20, 16, v88
	v_and_b32_e32 v21, 0xffff0000, v88
	v_lshlrev_b32_e32 v22, 16, v89
	v_and_b32_e32 v23, 0xffff0000, v89
	v_pk_mul_f32 v[16:17], v[30:31], v[16:17] op_sel_hi:[0,1]
	v_pk_mul_f32 v[18:19], v[30:31], v[18:19] op_sel_hi:[0,1]
	v_pk_mul_f32 v[20:21], v[30:31], v[20:21] op_sel_hi:[0,1]
	v_pk_mul_f32 v[22:23], v[30:31], v[22:23] op_sel_hi:[0,1]
	v_pk_mul_f32 v[16:17], v[32:33], v[16:17]
	v_pk_mul_f32 v[18:19], v[34:35], v[18:19]
	v_pk_mul_f32 v[20:21], v[36:37], v[20:21]
	v_pk_mul_f32 v[22:23], v[38:39], v[22:23]
	global_store_dwordx4 v50, v[16:19], s[24:25] offset:0
	global_store_dwordx4 v50, v[20:23], s[24:25] offset:16
	s_nop 1
	v_lshlrev_b32_e32 v16, 16, v90
	v_and_b32_e32 v17, 0xffff0000, v90
	v_lshlrev_b32_e32 v18, 16, v91
	v_and_b32_e32 v19, 0xffff0000, v91
	v_lshlrev_b32_e32 v20, 16, v92
	v_and_b32_e32 v21, 0xffff0000, v92
	v_lshlrev_b32_e32 v22, 16, v93
	v_and_b32_e32 v23, 0xffff0000, v93
	v_pk_mul_f32 v[16:17], v[30:31], v[16:17] op_sel_hi:[0,1]
	v_pk_mul_f32 v[18:19], v[30:31], v[18:19] op_sel_hi:[0,1]
	v_pk_mul_f32 v[20:21], v[30:31], v[20:21] op_sel_hi:[0,1]
	v_pk_mul_f32 v[22:23], v[30:31], v[22:23] op_sel_hi:[0,1]
	v_pk_mul_f32 v[16:17], v[40:41], v[16:17]
	v_pk_mul_f32 v[18:19], v[42:43], v[18:19]
	v_pk_mul_f32 v[20:21], v[44:45], v[20:21]
	v_pk_mul_f32 v[22:23], v[46:47], v[22:23]
	global_store_dwordx4 v50, v[16:19], s[24:25] offset:2048
	global_store_dwordx4 v50, v[20:23], s[24:25] offset:2064
	s_nop 1
	v_ffbh_u32_e32 v24, v95
	v_min_u32_e32 v24, 32, v24
	v_lshlrev_b64 v[94:95], v24, v[94:95]
	v_min_u32_e32 v94, 1, v94
	v_or_b32_e32 v95, v95, v94
	v_cvt_f32_u32_e32 v95, v95
	v_sub_u32_e32 v24, 32, v24
	v_ldexp_f32 v95, v95, v24
	v_fmamk_f32 v95, v95, 0x2e800000, v8
	v_rsq_f32_e32 v30, v95
	v_lshlrev_b32_e32 v16, 16, v96
	v_and_b32_e32 v17, 0xffff0000, v96
	v_lshlrev_b32_e32 v18, 16, v97
	v_and_b32_e32 v19, 0xffff0000, v97
	v_lshlrev_b32_e32 v20, 16, v98
	v_and_b32_e32 v21, 0xffff0000, v98
	v_lshlrev_b32_e32 v22, 16, v99
	v_and_b32_e32 v23, 0xffff0000, v99
	v_pk_mul_f32 v[16:17], v[30:31], v[16:17] op_sel_hi:[0,1]
	v_pk_mul_f32 v[18:19], v[30:31], v[18:19] op_sel_hi:[0,1]
	v_pk_mul_f32 v[20:21], v[30:31], v[20:21] op_sel_hi:[0,1]
	v_pk_mul_f32 v[22:23], v[30:31], v[22:23] op_sel_hi:[0,1]
	v_pk_mul_f32 v[16:17], v[32:33], v[16:17]
	v_pk_mul_f32 v[18:19], v[34:35], v[18:19]
	v_pk_mul_f32 v[20:21], v[36:37], v[20:21]
	v_pk_mul_f32 v[22:23], v[38:39], v[22:23]
	global_store_dwordx4 v50, v[16:19], s[26:27] offset:0
	global_store_dwordx4 v50, v[20:23], s[26:27] offset:16
	s_nop 1
	v_lshlrev_b32_e32 v16, 16, v100
	v_and_b32_e32 v17, 0xffff0000, v100
	v_lshlrev_b32_e32 v18, 16, v101
	v_and_b32_e32 v19, 0xffff0000, v101
	v_lshlrev_b32_e32 v20, 16, v102
	v_and_b32_e32 v21, 0xffff0000, v102
	v_lshlrev_b32_e32 v22, 16, v103
	v_and_b32_e32 v23, 0xffff0000, v103
	v_pk_mul_f32 v[16:17], v[30:31], v[16:17] op_sel_hi:[0,1]
	v_pk_mul_f32 v[18:19], v[30:31], v[18:19] op_sel_hi:[0,1]
	v_pk_mul_f32 v[20:21], v[30:31], v[20:21] op_sel_hi:[0,1]
	v_pk_mul_f32 v[22:23], v[30:31], v[22:23] op_sel_hi:[0,1]
	v_pk_mul_f32 v[16:17], v[40:41], v[16:17]
	v_pk_mul_f32 v[18:19], v[42:43], v[18:19]
	v_pk_mul_f32 v[20:21], v[44:45], v[20:21]
	v_pk_mul_f32 v[22:23], v[46:47], v[22:23]
	global_store_dwordx4 v50, v[16:19], s[26:27] offset:2048
	global_store_dwordx4 v50, v[20:23], s[26:27] offset:2064
	s_nop 1
	s_cmp_eq_u32 s45, 0
	s_cbranch_scc1 .Lfn_tail
	s_add_u32 s8, s8, s47
	s_branch .Lfn_pb
.Lfn_pb:
	s_add_u32 s10, s8, s43
	s_cmp_lt_u32 s10, s44
	s_cselect_b32 s45, 1, 0
	s_sub_u32 s46, s8, s47
	s_cmp_eq_u32 s45, 1
	s_cselect_b32 s46, s8, s46
	s_mov_b32 s11, s46
	s_lshl_b32 s37, s11, 3
	s_add_u32 s38, s0, s37
	s_addc_u32 s39, s1, 0
	global_load_dwordx2 v[64:65], v49, s[38:39]
	s_lshl_b32 s37, s11, 11
	s_add_u32 s38, s12, s37
	s_addc_u32 s39, s13, 0
	global_load_dwordx4 v[66:69], v48, s[38:39]
	global_load_dwordx4 v[70:73], v48, s[38:39] offset:1024
	s_lshl_b32 s37, s11, 12
	s_add_u32 s20, s16, s37
	s_addc_u32 s21, s17, 0
	s_add_u32 s11, s46, s41
	s_lshl_b32 s37, s11, 3
	s_add_u32 s38, s0, s37
	s_addc_u32 s39, s1, 0
	global_load_dwordx2 v[74:75], v49, s[38:39]
	s_lshl_b32 s37, s11, 11
	s_add_u32 s38, s12, s37
	s_addc_u32 s39, s13, 0
	global_load_dwordx4 v[76:79], v48, s[38:39]
	global_load_dwordx4 v[80:83], v48, s[38:39] offset:1024
	s_lshl_b32 s37, s11, 12
	s_add_u32 s22, s16, s37
	s_addc_u32 s23, s17, 0
	s_add_u32 s11, s46, s42
	s_lshl_b32 s37, s11, 3
	s_add_u32 s38, s0, s37
	s_addc_u32 s39, s1, 0
	global_load_dwordx2 v[84:85], v49, s[38:39]
	s_lshl_b32 s37, s11, 11
	s_add_u32 s38, s12, s37
	s_addc_u32 s39, s13, 0
	global_load_dwordx4 v[86:89], v48, s[38:39]
	global_load_dwordx4 v[90:93], v48, s[38:39] offset:1024
	s_lshl_b32 s37, s11, 12
	s_add_u32 s24, s16, s37
	s_addc_u32 s25, s17, 0
	s_add_u32 s11, s46, s43
	s_lshl_b32 s37, s11, 3
	s_add_u32 s38, s0, s37
	s_addc_u32 s39, s1, 0
	global_load_dwordx2 v[94:95], v49, s[38:39]
	s_lshl_b32 s37, s11, 11
	s_add_u32 s38, s12, s37
	s_addc_u32 s39, s13, 0
	global_load_dwordx4 v[96:99], v48, s[38:39]
	global_load_dwordx4 v[100:103], v48, s[38:39] offset:1024
	s_lshl_b32 s37, s11, 12
	s_add_u32 s26, s16, s37
	s_addc_u32 s27, s17, 0
	s_cmp_eq_u32 s36, 1
	s_cbranch_scc1 .Lfn_pb_w12
	s_waitcnt vmcnt(28)
	s_branch .Lfn_pb_go

.Lfn_pb_go:
	s_mov_b32 s36, 0
	v_ffbh_u32_e32 v24, v105
	v_min_u32_e32 v24, 32, v24
	v_lshlrev_b64 v[104:105], v24, v[104:105]
	v_min_u32_e32 v104, 1, v104
	v_or_b32_e32 v105, v105, v104
	v_cvt_f32_u32_e32 v105, v105
	v_sub_u32_e32 v24, 32, v24
	v_ldexp_f32 v105, v105, v24
	v_fmamk_f32 v105, v105, 0x2e800000, v8
	v_rsq_f32_e32 v30, v105
	v_lshlrev_b32_e32 v16, 16, v106
	v_and_b32_e32 v17, 0xffff0000, v106
	v_lshlrev_b32_e32 v18, 16, v107
	v_and_b32_e32 v19, 0xffff0000, v107
	v_lshlrev_b32_e32 v20, 16, v108
	v_and_b32_e32 v21, 0xffff0000, v108
	v_lshlrev_b32_e32 v22, 16, v109
	v_and_b32_e32 v23, 0xffff0000, v109
	v_pk_mul_f32 v[16:17], v[30:31], v[16:17] op_sel_hi:[0,1]
	v_pk_mul_f32 v[18:19], v[30:31], v[18:19] op_sel_hi:[0,1]
	v_pk_mul_f32 v[20:21], v[30:31], v[20:21] op_sel_hi:[0,1]
	v_pk_mul_f32 v[22:23], v[30:31], v[22:23] op_sel_hi:[0,1]
	v_pk_mul_f32 v[16:17], v[32:33], v[16:17]
	v_pk_mul_f32 v[18:19], v[34:35], v[18:19]
	v_pk_mul_f32 v[20:21], v[36:37], v[20:21]
	v_pk_mul_f32 v[22:23], v[38:39], v[22:23]
	global_store_dwordx4 v50, v[16:19], s[28:29] offset:0
	global_store_dwordx4 v50, v[20:23], s[28:29] offset:16
	s_nop 1
	v_lshlrev_b32_e32 v16, 16, v110
	v_and_b32_e32 v17, 0xffff0000, v110
	v_lshlrev_b32_e32 v18, 16, v111
	v_and_b32_e32 v19, 0xffff0000, v111
	v_lshlrev_b32_e32 v20, 16, v112
	v_and_b32_e32 v21, 0xffff0000, v112
	v_lshlrev_b32_e32 v22, 16, v113
	v_and_b32_e32 v23, 0xffff0000, v113
	v_pk_mul_f32 v[16:17], v[30:31], v[16:17] op_sel_hi:[0,1]
	v_pk_mul_f32 v[18:19], v[30:31], v[18:19] op_sel_hi:[0,1]
	v_pk_mul_f32 v[20:21], v[30:31], v[20:21] op_sel_hi:[0,1]
	v_pk_mul_f32 v[22:23], v[30:31], v[22:23] op_sel_hi:[0,1]
	v_pk_mul_f32 v[16:17], v[40:41], v[16:17]
	v_pk_mul_f32 v[18:19], v[42:43], v[18:19]
	v_pk_mul_f32 v[20:21], v[44:45], v[20:21]
	v_pk_mul_f32 v[22:23], v[46:47], v[22:23]
	global_store_dwordx4 v50, v[16:19], s[28:29] offset:2048
	global_store_dwordx4 v50, v[20:23], s[28:29] offset:2064
	s_nop 1
	v_ffbh_u32_e32 v24, v115
	v_min_u32_e32 v24, 32, v24
	v_lshlrev_b64 v[114:115], v24, v[114:115]
	v_min_u32_e32 v114, 1, v114
	v_or_b32_e32 v115, v115, v114
	v_cvt_f32_u32_e32 v115, v115
	v_sub_u32_e32 v24, 32, v24
	v_ldexp_f32 v115, v115, v24
	v_fmamk_f32 v115, v115, 0x2e800000, v8
	v_rsq_f32_e32 v30, v115
	v_lshlrev_b32_e32 v16, 16, v116
	v_and_b32_e32 v17, 0xffff0000, v116
	v_lshlrev_b32_e32 v18, 16, v117
	v_and_b32_e32 v19, 0xffff0000, v117
	v_lshlrev_b32_e32 v20, 16, v118
	v_and_b32_e32 v21, 0xffff0000, v118
	v_lshlrev_b32_e32 v22, 16, v119
	v_and_b32_e32 v23, 0xffff0000, v119
	v_pk_mul_f32 v[16:17], v[30:31], v[16:17] op_sel_hi:[0,1]
	v_pk_mul_f32 v[18:19], v[30:31], v[18:19] op_sel_hi:[0,1]
	v_pk_mul_f32 v[20:21], v[30:31], v[20:21] op_sel_hi:[0,1]
	v_pk_mul_f32 v[22:23], v[30:31], v[22:23] op_sel_hi:[0,1]
	v_pk_mul_f32 v[16:17], v[32:33], v[16:17]
	v_pk_mul_f32 v[18:19], v[34:35], v[18:19]
	v_pk_mul_f32 v[20:21], v[36:37], v[20:21]
	v_pk_mul_f32 v[22:23], v[38:39], v[22:23]
	global_store_dwordx4 v50, v[16:19], s[30:31] offset:0
	global_store_dwordx4 v50, v[20:23], s[30:31] offset:16
	s_nop 1
	v_lshlrev_b32_e32 v16, 16, v120
	v_and_b32_e32 v17, 0xffff0000, v120
	v_lshlrev_b32_e32 v18, 16, v121
	v_and_b32_e32 v19, 0xffff0000, v121
	v_lshlrev_b32_e32 v20, 16, v122
	v_and_b32_e32 v21, 0xffff0000, v122
	v_lshlrev_b32_e32 v22, 16, v123
	v_and_b32_e32 v23, 0xffff0000, v123
	v_pk_mul_f32 v[16:17], v[30:31], v[16:17] op_sel_hi:[0,1]
	v_pk_mul_f32 v[18:19], v[30:31], v[18:19] op_sel_hi:[0,1]
	v_pk_mul_f32 v[20:21], v[30:31], v[20:21] op_sel_hi:[0,1]
	v_pk_mul_f32 v[22:23], v[30:31], v[22:23] op_sel_hi:[0,1]
	v_pk_mul_f32 v[16:17], v[40:41], v[16:17]
	v_pk_mul_f32 v[18:19], v[42:43], v[18:19]
	v_pk_mul_f32 v[20:21], v[44:45], v[20:21]
	v_pk_mul_f32 v[22:23], v[46:47], v[22:23]
	global_store_dwordx4 v50, v[16:19], s[30:31] offset:2048
	global_store_dwordx4 v50, v[20:23], s[30:31] offset:2064
	s_nop 1
	v_ffbh_u32_e32 v24, v125
	v_min_u32_e32 v24, 32, v24
	v_lshlrev_b64 v[124:125], v24, v[124:125]
	v_min_u32_e32 v124, 1, v124
	v_or_b32_e32 v125, v125, v124
	v_cvt_f32_u32_e32 v125, v125
	v_sub_u32_e32 v24, 32, v24
	v_ldexp_f32 v125, v125, v24
	v_fmamk_f32 v125, v125, 0x2e800000, v8
	v_rsq_f32_e32 v30, v125
	v_lshlrev_b32_e32 v16, 16, v126
	v_and_b32_e32 v17, 0xffff0000, v126
	v_lshlrev_b32_e32 v18, 16, v127
	v_and_b32_e32 v19, 0xffff0000, v127
	v_lshlrev_b32_e32 v20, 16, v128
	v_and_b32_e32 v21, 0xffff0000, v128
	v_lshlrev_b32_e32 v22, 16, v129
	v_and_b32_e32 v23, 0xffff0000, v129
	v_pk_mul_f32 v[16:17], v[30:31], v[16:17] op_sel_hi:[0,1]
	v_pk_mul_f32 v[18:19], v[30:31], v[18:19] op_sel_hi:[0,1]
	v_pk_mul_f32 v[20:21], v[30:31], v[20:21] op_sel_hi:[0,1]
	v_pk_mul_f32 v[22:23], v[30:31], v[22:23] op_sel_hi:[0,1]
	v_pk_mul_f32 v[16:17], v[32:33], v[16:17]
	v_pk_mul_f32 v[18:19], v[34:35], v[18:19]
	v_pk_mul_f32 v[20:21], v[36:37], v[20:21]
	v_pk_mul_f32 v[22:23], v[38:39], v[22:23]
	global_store_dwordx4 v50, v[16:19], s[32:33] offset:0
	global_store_dwordx4 v50, v[20:23], s[32:33] offset:16
	s_nop 1
	v_lshlrev_b32_e32 v16, 16, v130
	v_and_b32_e32 v17, 0xffff0000, v130
	v_lshlrev_b32_e32 v18, 16, v131
	v_and_b32_e32 v19, 0xffff0000, v131
	v_lshlrev_b32_e32 v20, 16, v132
	v_and_b32_e32 v21, 0xffff0000, v132
	v_lshlrev_b32_e32 v22, 16, v133
	v_and_b32_e32 v23, 0xffff0000, v133
	v_pk_mul_f32 v[16:17], v[30:31], v[16:17] op_sel_hi:[0,1]
	v_pk_mul_f32 v[18:19], v[30:31], v[18:19] op_sel_hi:[0,1]
	v_pk_mul_f32 v[20:21], v[30:31], v[20:21] op_sel_hi:[0,1]
	v_pk_mul_f32 v[22:23], v[30:31], v[22:23] op_sel_hi:[0,1]
	v_pk_mul_f32 v[16:17], v[40:41], v[16:17]
	v_pk_mul_f32 v[18:19], v[42:43], v[18:19]
	v_pk_mul_f32 v[20:21], v[44:45], v[20:21]
	v_pk_mul_f32 v[22:23], v[46:47], v[22:23]
	global_store_dwordx4 v50, v[16:19], s[32:33] offset:2048
	global_store_dwordx4 v50, v[20:23], s[32:33] offset:2064
	s_nop 1
	v_ffbh_u32_e32 v24, v135
	v_min_u32_e32 v24, 32, v24
	v_lshlrev_b64 v[134:135], v24, v[134:135]
	v_min_u32_e32 v134, 1, v134
	v_or_b32_e32 v135, v135, v134
	v_cvt_f32_u32_e32 v135, v135
	v_sub_u32_e32 v24, 32, v24
	v_ldexp_f32 v135, v135, v24
	v_fmamk_f32 v135, v135, 0x2e800000, v8
	v_rsq_f32_e32 v30, v135
	v_lshlrev_b32_e32 v16, 16, v136
	v_and_b32_e32 v17, 0xffff0000, v136
	v_lshlrev_b32_e32 v18, 16, v137
	v_and_b32_e32 v19, 0xffff0000, v137
	v_lshlrev_b32_e32 v20, 16, v138
	v_and_b32_e32 v21, 0xffff0000, v138
	v_lshlrev_b32_e32 v22, 16, v139
	v_and_b32_e32 v23, 0xffff0000, v139
	v_pk_mul_f32 v[16:17], v[30:31], v[16:17] op_sel_hi:[0,1]
	v_pk_mul_f32 v[18:19], v[30:31], v[18:19] op_sel_hi:[0,1]
	v_pk_mul_f32 v[20:21], v[30:31], v[20:21] op_sel_hi:[0,1]
	v_pk_mul_f32 v[22:23], v[30:31], v[22:23] op_sel_hi:[0,1]
	v_pk_mul_f32 v[16:17], v[32:33], v[16:17]
	v_pk_mul_f32 v[18:19], v[34:35], v[18:19]
	v_pk_mul_f32 v[20:21], v[36:37], v[20:21]
	v_pk_mul_f32 v[22:23], v[38:39], v[22:23]
	global_store_dwordx4 v50, v[16:19], s[34:35] offset:0
	global_store_dwordx4 v50, v[20:23], s[34:35] offset:16
	s_nop 1
	v_lshlrev_b32_e32 v16, 16, v140
	v_and_b32_e32 v17, 0xffff0000, v140
	v_lshlrev_b32_e32 v18, 16, v141
	v_and_b32_e32 v19, 0xffff0000, v141
	v_lshlrev_b32_e32 v20, 16, v142
	v_and_b32_e32 v21, 0xffff0000, v142
	v_lshlrev_b32_e32 v22, 16, v143
	v_and_b32_e32 v23, 0xffff0000, v143
	v_pk_mul_f32 v[16:17], v[30:31], v[16:17] op_sel_hi:[0,1]
	v_pk_mul_f32 v[18:19], v[30:31], v[18:19] op_sel_hi:[0,1]
	v_pk_mul_f32 v[20:21], v[30:31], v[20:21] op_sel_hi:[0,1]
	v_pk_mul_f32 v[22:23], v[30:31], v[22:23] op_sel_hi:[0,1]
	v_pk_mul_f32 v[16:17], v[40:41], v[16:17]
	v_pk_mul_f32 v[18:19], v[42:43], v[18:19]
	v_pk_mul_f32 v[20:21], v[44:45], v[20:21]
	v_pk_mul_f32 v[22:23], v[46:47], v[22:23]
	global_store_dwordx4 v50, v[16:19], s[34:35] offset:2048
	global_store_dwordx4 v50, v[20:23], s[34:35] offset:2064
	s_nop 1
	s_cmp_eq_u32 s45, 0
	s_cbranch_scc1 .Lfn_tail
	s_add_u32 s8, s8, s47
	s_branch .Lfn_pa
.Lfn_tail:
.Lfn_skip:
	v_mov_b32_e32 v0, s8
	s_nop 1
	v_cmp_gt_i32_e32 vcc, s44, v0
	s_and_b64 exec, exec, vcc
	s_mov_b64 s[2:3], 0
	s_cbranch_execz .LBB0_2131
